# attention loop: packed f32 VALU ops replaced by plain f32 ops next to MFMAs
# speedup vs baseline: 1.0066x; 1.0003x over previous
; __device__ __forceinline__ void attn_tile(int t, int buf, LAS unsigned char* lds, const bf16x8 (&qr)[4], float cq2, int qlo, int qpos, int q32, int hi,
;                                           float& mrun, float& lrun, f32x16& o0, f32x16& o1) {
;     ...
; #pragma unroll
;     for (int d0 = 0; d0 < 4; ++d0) {
;         const bf16x8 k0 = *(const LAS bf16x8*)(Kt + q32 * 144 + d0 * 32 + hi * 16);
;         const bf16x8 k1 = *(const LAS bf16x8*)(Kt + (32 + q32) * 144 + d0 * 32 + hi * 16);
;         s0 = __builtin_amdgcn_mfma_f32_32x32x16_bf16(k0, qr[d0], s0, 0, 0, 0);
;         s1 = __builtin_amdgcn_mfma_f32_32x32x16_bf16(k1, qr[d0], s1, 0, 0, 0);
;     }
;     ...
;     f32x2 ls2 = (f32x2){0.f, 0.f};
; #pragma unroll
;     for (int r = 0; r < 16; r += 2) {
;         const f32x2 d0 = (f32x2){s0[r], s0[r + 1]} - mnew, d1 = (f32x2){s1[r], s1[r + 1]} - mnew;
;         f32x2 e0, e1; e0.x = fexp2(d0.x); e0.y = fexp2(d0.y); e1.x = fexp2(d1.x); e1.y = fexp2(d1.y);
;         s0[r] = e0.x; s0[r + 1] = e0.y; s1[r] = e1.x; s1[r + 1] = e1.y;
;         ls2 += e0 + e1;
;     }
;     lrun += ls2.x + ls2.y;
; #pragma unroll
;     for (int p = 0; p < 2; ++p)
; #pragma unroll
;         for (int sx = 0; sx < 2; ++sx) {
;             u32x4 pw;
;             if (p == 0) pw = (u32x4){pk_bf16(s0[8 * sx + 0], s0[8 * sx + 1]), pk_bf16(s0[8 * sx + 2], s0[8 * sx + 3]), pk_bf16(s0[8 * sx + 4], s0[8 * sx + 5]), pk_bf16(s0[8 * sx + 6], s0[8 * sx + 7])};
;             else        pw = (u32x4){pk_bf16(s1[8 * sx + 0], s1[8 * sx + 1]), pk_bf16(s1[8 * sx + 2], s1[8 * sx + 3]), pk_bf16(s1[8 * sx + 4], s1[8 * sx + 5]), pk_bf16(s1[8 * sx + 6], s1[8 * sx + 7])};
;             const bf16x8 pf = __builtin_bit_cast(bf16x8, pw);
;             const int ko = (32 * p + 16 * sx + 4 * hi) * 2;
;             const u32x2 a0 = *(const LAS u32x2*)(Vt + q32 * 136 + ko), a1 = *(const LAS u32x2*)(Vt + q32 * 136 + ko + 16);
;             const u32x2 b0 = *(const LAS u32x2*)(Vt + (32 + q32) * 136 + ko), b1 = *(const LAS u32x2*)(Vt + (32 + q32) * 136 + ko + 16);
;             const bf16x8 vf0 = __builtin_bit_cast(bf16x8, (u32x4){a0.x, a0.y, a1.x, a1.y});
;             const bf16x8 vf1 = __builtin_bit_cast(bf16x8, (u32x4){b0.x, b0.y, b1.x, b1.y});
;             o0 = __builtin_amdgcn_mfma_f32_32x32x16_bf16(vf0, pf, o0, 0, 0, 0);
;             o1 = __builtin_amdgcn_mfma_f32_32x32x16_bf16(vf1, pf, o1, 0, 0, 0);
;         }
.LnoV_E:
	s_waitcnt lgkmcnt(0)
	s_barrier
	s_add_i32 s6, s22, 2
	s_lshl_b32 s6, s6, 18
	s_add_u32 s98, s8, s6
	s_addc_u32 s99, s9, 0
	global_load_dwordx4 v[82:85], v158, s[98:99] offset:1024
	s_sub_u32 s100, s98, 0x40000
	s_subb_u32 s101, s99, 0
	global_load_dwordx4 v[94:97], v158, s[100:101] offset:2048
	s_lshl_b32 s6, s22, 6
	s_cmp_le_i32 s6, s23
	s_cbranch_scc0 .Lnoproc_E
	ds_read_b128 v[124:127], v112 offset:8448
	ds_read_b128 v[34:37], v111
	ds_read_b128 v[38:41], v111 offset:32
	ds_read_b128 v[42:45], v111 offset:64
	ds_read_b128 v[46:49], v111 offset:96
	ds_read_b128 v[128:131], v112 offset:13056
	ds_read_b128 v[50:53], v111 offset:128
	ds_read_b128 v[54:57], v111 offset:160
	ds_read_b128 v[58:61], v111 offset:192
	ds_read_b128 v[62:65], v111 offset:224
	ds_read_b128 v[132:135], v112 offset:8480
	ds_read_b128 v[136:139], v112 offset:13088
	ds_read_b128 v[140:143], v112 offset:8512
	ds_read_b128 v[144:147], v112 offset:13120
	s_cmp_eq_u32 s27, 0
	s_cbranch_scc1 .Lqkonly_E
	v_sub_f32_e32 v206, v206, v114
	v_sub_f32_e32 v207, v207, v114
	v_sub_f32_e32 v208, v208, v114
	v_sub_f32_e32 v209, v209, v114
	v_sub_f32_e32 v210, v210, v114
	v_sub_f32_e32 v211, v211, v114
	v_sub_f32_e32 v212, v212, v114
	v_sub_f32_e32 v213, v213, v114
	v_exp_f32_e32 v206, v206
	v_exp_f32_e32 v207, v207
	v_exp_f32_e32 v208, v208
	v_exp_f32_e32 v209, v209
	v_exp_f32_e32 v210, v210
	v_exp_f32_e32 v211, v211
	v_exp_f32_e32 v212, v212
	v_exp_f32_e32 v213, v213
	v_cvt_pk_bf16_f32 v118, v206, v207
	v_cvt_pk_bf16_f32 v119, v208, v209
	v_cvt_pk_bf16_f32 v120, v210, v211
	v_cvt_pk_bf16_f32 v121, v212, v213
	v_add_f32_e32 v116, v206, v208
	v_add_f32_e32 v117, v207, v209
	v_add_f32_e32 v116, v116, v210
	v_add_f32_e32 v117, v117, v211
	v_add_f32_e32 v116, v116, v212
	v_add_f32_e32 v117, v117, v213
	s_waitcnt lgkmcnt(9)
	v_mfma_f32_32x32x16_bf16 v[34:49], v[124:127], v[78:81], v[34:49]
	ds_read_b128 v[148:151], v112 offset:8544
	ds_read_b128 v[152:155], v112 offset:13152
	s_waitcnt lgkmcnt(6)
	v_mfma_f32_32x32x16_bf16 v[50:65], v[128:131], v[78:81], v[50:65]
	s_waitcnt lgkmcnt(5)
	v_mfma_f32_32x32x16_bf16 v[34:49], v[132:135], v[74:77], v[34:49]
	s_waitcnt lgkmcnt(4)
	v_mfma_f32_32x32x16_bf16 v[50:65], v[136:139], v[74:77], v[50:65]
	s_waitcnt lgkmcnt(3)
	v_mfma_f32_32x32x16_bf16 v[34:49], v[140:143], v[70:73], v[34:49]
	s_waitcnt lgkmcnt(2)
	v_mfma_f32_32x32x16_bf16 v[50:65], v[144:147], v[70:73], v[50:65]
	s_waitcnt lgkmcnt(1)
	v_mfma_f32_32x32x16_bf16 v[34:49], v[148:151], v[66:69], v[34:49]
	s_waitcnt lgkmcnt(0)
	v_mfma_f32_32x32x16_bf16 v[50:65], v[152:155], v[66:69], v[50:65]
	v_add_u32_e32 v122, 0x8800, v113
	v_add_u32_e32 v123, 0x9800, v113
	ds_read2_b64 v[166:169], v122 offset0:96 offset1:98
	ds_read2_b64 v[170:173], v123 offset0:128 offset1:130
	ds_read2_b64 v[174:177], v122 offset0:100 offset1:102
	ds_read2_b64 v[178:181], v123 offset0:132 offset1:134
	ds_read2_b64 v[182:185], v122 offset0:104 offset1:106
	ds_read2_b64 v[186:189], v123 offset0:136 offset1:138
	ds_read2_b64 v[190:193], v122 offset0:108 offset1:110
	ds_read2_b64 v[194:197], v123 offset0:140 offset1:142
	v_sub_f32_e32 v214, v214, v114
	v_sub_f32_e32 v215, v215, v114
	v_sub_f32_e32 v216, v216, v114
	v_sub_f32_e32 v217, v217, v114
	v_sub_f32_e32 v218, v218, v114
	v_sub_f32_e32 v219, v219, v114
	v_sub_f32_e32 v220, v220, v114
	v_sub_f32_e32 v221, v221, v114
	v_exp_f32_e32 v214, v214
	v_exp_f32_e32 v215, v215
	v_exp_f32_e32 v216, v216
	v_exp_f32_e32 v217, v217
	v_exp_f32_e32 v218, v218
	v_exp_f32_e32 v219, v219
	v_exp_f32_e32 v220, v220
	v_exp_f32_e32 v221, v221
	s_waitcnt lgkmcnt(0)
	v_mfma_f32_32x32x16_bf16 v[18:33], v[166:169], v[118:121], v[18:33]
	v_mfma_f32_32x32x16_bf16 v[2:17], v[170:173], v[118:121], v[2:17]
	v_cvt_pk_bf16_f32 v118, v214, v215
	v_cvt_pk_bf16_f32 v119, v216, v217
	v_cvt_pk_bf16_f32 v120, v218, v219
	v_cvt_pk_bf16_f32 v121, v220, v221
	v_add_f32_e32 v116, v116, v214
	v_add_f32_e32 v117, v117, v215
	v_add_f32_e32 v116, v116, v216
	v_add_f32_e32 v117, v117, v217
	v_add_f32_e32 v116, v116, v218
	v_add_f32_e32 v117, v117, v219
	v_add_f32_e32 v116, v116, v220
	v_add_f32_e32 v117, v117, v221
	v_mfma_f32_32x32x16_bf16 v[18:33], v[174:177], v[118:121], v[18:33]
	v_mfma_f32_32x32x16_bf16 v[2:17], v[178:181], v[118:121], v[2:17]
	v_sub_f32_e32 v222, v222, v114
	v_sub_f32_e32 v223, v223, v114
	v_sub_f32_e32 v224, v224, v114
	v_sub_f32_e32 v225, v225, v114
	v_sub_f32_e32 v226, v226, v114
	v_sub_f32_e32 v227, v227, v114
	v_sub_f32_e32 v228, v228, v114
	v_sub_f32_e32 v229, v229, v114
	v_exp_f32_e32 v222, v222
	v_exp_f32_e32 v223, v223
	v_exp_f32_e32 v224, v224
	v_exp_f32_e32 v225, v225
	v_exp_f32_e32 v226, v226
	v_exp_f32_e32 v227, v227
	v_exp_f32_e32 v228, v228
	v_exp_f32_e32 v229, v229
	v_cvt_pk_bf16_f32 v118, v222, v223
	v_cvt_pk_bf16_f32 v119, v224, v225
	v_cvt_pk_bf16_f32 v120, v226, v227
	v_cvt_pk_bf16_f32 v121, v228, v229
	v_add_f32_e32 v116, v116, v222
	v_add_f32_e32 v117, v117, v223
	v_add_f32_e32 v116, v116, v224
	v_add_f32_e32 v117, v117, v225
	v_add_f32_e32 v116, v116, v226
	v_add_f32_e32 v117, v117, v227
	v_add_f32_e32 v116, v116, v228
	v_add_f32_e32 v117, v117, v229
	v_mfma_f32_32x32x16_bf16 v[18:33], v[182:185], v[118:121], v[18:33]
	v_mfma_f32_32x32x16_bf16 v[2:17], v[186:189], v[118:121], v[2:17]
	v_sub_f32_e32 v230, v230, v114
	v_sub_f32_e32 v231, v231, v114
	v_sub_f32_e32 v232, v232, v114
	v_sub_f32_e32 v233, v233, v114
	v_sub_f32_e32 v234, v234, v114
	v_sub_f32_e32 v235, v235, v114
	v_sub_f32_e32 v236, v236, v114
	v_sub_f32_e32 v237, v237, v114
	v_exp_f32_e32 v230, v230
	v_exp_f32_e32 v231, v231
	v_exp_f32_e32 v232, v232
	v_exp_f32_e32 v233, v233
	v_exp_f32_e32 v234, v234
	v_exp_f32_e32 v235, v235
	v_exp_f32_e32 v236, v236
	v_exp_f32_e32 v237, v237
	v_cvt_pk_bf16_f32 v118, v230, v231
	v_cvt_pk_bf16_f32 v119, v232, v233
	v_cvt_pk_bf16_f32 v120, v234, v235
	v_cvt_pk_bf16_f32 v121, v236, v237
	v_add_f32_e32 v116, v116, v230
	v_add_f32_e32 v117, v117, v231
	v_add_f32_e32 v116, v116, v232
	v_add_f32_e32 v117, v117, v233
	v_add_f32_e32 v116, v116, v234
	v_add_f32_e32 v117, v117, v235
	v_add_f32_e32 v116, v116, v236
	v_add_f32_e32 v117, v117, v237
	v_mfma_f32_32x32x16_bf16 v[18:33], v[190:193], v[118:121], v[18:33]
	v_mfma_f32_32x32x16_bf16 v[2:17], v[194:197], v[118:121], v[2:17]
	v_add_f32_e32 v116, v116, v117
	v_add_f32_e32 v109, v109, v116
	s_branch .Lmax_E

; __device__ __forceinline__ float fexp2(float x) { return __builtin_amdgcn_exp2f(x); }
; __device__ __forceinline__ void attn_tile(int t, int buf, LAS unsigned char* lds, const bf16x8 (&qr)[4], float cq2, int qlo, int qpos, int q32, int hi,
;                                           float& mrun, float& lrun, f32x16& o0, f32x16& o1) {
;     ...
;     float mx = fmaxf(s0[0], s1[0]);
; #pragma unroll
;     for (int r = 1; r < 16; ++r) mx = fmaxf(mx, fmaxf(s0[r], s1[r]));
;     mx = fmaxf(mx, __shfl_xor(mx, 32));
;     const float mnew = fmaxf(mrun, mx);
;     if (__any(mnew > mrun)) {
;         const float alpha = fexp2(mrun - mnew); lrun *= alpha;
; #pragma unroll
;         for (int r = 0; r < 16; ++r) { o0[r] *= alpha; o1[r] *= alpha; }
;     }
;     mrun = mnew;
.Lnomask_E:
	v_max3_f32 v0, v34, v50, v35
	v_max3_f32 v115, v51, v36, v52
	v_max3_f32 v0, v0, v37, v53
	v_max3_f32 v115, v115, v38, v54
	v_max3_f32 v0, v0, v39, v55
	v_max3_f32 v115, v115, v40, v56
	v_max3_f32 v0, v0, v41, v57
	v_max3_f32 v115, v115, v42, v58
	v_max3_f32 v0, v0, v43, v59
	v_max3_f32 v115, v115, v44, v60
	v_max3_f32 v0, v0, v45, v61
	v_max3_f32 v115, v115, v46, v62
	v_max3_f32 v0, v0, v47, v63
	v_max3_f32 v115, v115, v48, v64
	v_max3_f32 v0, v0, v49, v65
	v_max_f32_e32 v0, v0, v115
	ds_bpermute_b32 v115, v107, v0
	s_waitcnt lgkmcnt(0)
	v_max3_f32 v0, v114, v0, v115
	v_add_f32_e32 v115, 0x41c00000, v114
	v_cmp_gt_f32_e32 vcc, v0, v115
	s_cbranch_vccz .Lnoresc_E
	v_sub_f32_e32 v114, v114, v0
	v_exp_f32_e32 v114, v114
	s_nop 0
	v_mul_f32_e32 v109, v109, v114
	v_mul_f32_e32 v33, v33, v114
	v_mul_f32_e32 v32, v32, v114
	v_mul_f32_e32 v31, v31, v114
	v_mul_f32_e32 v30, v30, v114
	v_mul_f32_e32 v29, v29, v114
	v_mul_f32_e32 v28, v28, v114
	v_mul_f32_e32 v27, v27, v114
	v_mul_f32_e32 v26, v26, v114
	v_mul_f32_e32 v25, v25, v114
	v_mul_f32_e32 v24, v24, v114
	v_mul_f32_e32 v23, v23, v114
	v_mul_f32_e32 v22, v22, v114
	v_mul_f32_e32 v21, v21, v114
	v_mul_f32_e32 v20, v20, v114
	v_mul_f32_e32 v19, v19, v114
	v_mul_f32_e32 v18, v18, v114
	v_mul_f32_e32 v17, v17, v114
	v_mul_f32_e32 v16, v16, v114
	v_mul_f32_e32 v15, v15, v114
	v_mul_f32_e32 v14, v14, v114
	v_mul_f32_e32 v13, v13, v114
	v_mul_f32_e32 v12, v12, v114
	v_mul_f32_e32 v11, v11, v114
	v_mul_f32_e32 v10, v10, v114
	v_mul_f32_e32 v9, v9, v114
	v_mul_f32_e32 v8, v8, v114
	v_mul_f32_e32 v7, v7, v114
	v_mul_f32_e32 v6, v6, v114
	v_mul_f32_e32 v5, v5, v114
	v_mul_f32_e32 v4, v4, v114
	v_mul_f32_e32 v3, v3, v114
	v_mul_f32_e32 v2, v2, v114
	v_mov_b32_e32 v114, v0

; #define LAS __attribute__((address_space(3)))
; __device__ __forceinline__ unsigned pk_bf16(float lo, float hi) { const f32x2_t v = {lo, hi}; const bf16x2_t b = __builtin_convertvector(v, bf16x2_t); return __builtin_bit_cast(unsigned, b); }
; __device__ __forceinline__ float fexp2(float x) { return __builtin_amdgcn_exp2f(x); }
; __device__ __forceinline__ void attn_tile(int t, int buf, LAS unsigned char* lds, const bf16x8 (&qr)[4], float cq2, int qlo, int qpos, int q32, int hi,
;                                           float& mrun, float& lrun, f32x16& o0, f32x16& o1) {
;     ...
;     f32x2 ls2 = (f32x2){0.f, 0.f};
; #pragma unroll
;     for (int r = 0; r < 16; r += 2) {
;         const f32x2 d0 = (f32x2){s0[r], s0[r + 1]} - mnew, d1 = (f32x2){s1[r], s1[r + 1]} - mnew;
;         f32x2 e0, e1; e0.x = fexp2(d0.x); e0.y = fexp2(d0.y); e1.x = fexp2(d1.x); e1.y = fexp2(d1.y);
;         s0[r] = e0.x; s0[r + 1] = e0.y; s1[r] = e1.x; s1[r + 1] = e1.y;
;         ls2 += e0 + e1;
;     }
;     lrun += ls2.x + ls2.y;
; #pragma unroll
;     for (int p = 0; p < 2; ++p)
; #pragma unroll
;         for (int sx = 0; sx < 2; ++sx) {
;             u32x4 pw;
;             if (p == 0) pw = (u32x4){pk_bf16(s0[8 * sx + 0], s0[8 * sx + 1]), pk_bf16(s0[8 * sx + 2], s0[8 * sx + 3]), pk_bf16(s0[8 * sx + 4], s0[8 * sx + 5]), pk_bf16(s0[8 * sx + 6], s0[8 * sx + 7])};
;             else        pw = (u32x4){pk_bf16(s1[8 * sx + 0], s1[8 * sx + 1]), pk_bf16(s1[8 * sx + 2], s1[8 * sx + 3]), pk_bf16(s1[8 * sx + 4], s1[8 * sx + 5]), pk_bf16(s1[8 * sx + 6], s1[8 * sx + 7])};
;             const bf16x8 pf = __builtin_bit_cast(bf16x8, pw);
;             const int ko = (32 * p + 16 * sx + 4 * hi) * 2;
;             const u32x2 a0 = *(const LAS u32x2*)(Vt + q32 * 136 + ko), a1 = *(const LAS u32x2*)(Vt + q32 * 136 + ko + 16);
;             const u32x2 b0 = *(const LAS u32x2*)(Vt + (32 + q32) * 136 + ko), b1 = *(const LAS u32x2*)(Vt + (32 + q32) * 136 + ko + 16);
;             const bf16x8 vf0 = __builtin_bit_cast(bf16x8, (u32x4){a0.x, a0.y, a1.x, a1.y});
;             const bf16x8 vf1 = __builtin_bit_cast(bf16x8, (u32x4){b0.x, b0.y, b1.x, b1.y});
;             o0 = __builtin_amdgcn_mfma_f32_32x32x16_bf16(vf0, pf, o0, 0, 0, 0);
;             o1 = __builtin_amdgcn_mfma_f32_32x32x16_bf16(vf1, pf, o1, 0, 0, 0);
;         }
.Lnoproc_E:
	s_mov_b32 s26, 0
	s_cmp_eq_u32 s27, 0
	s_cbranch_scc1 .Lend_E
	v_add_u32_e32 v122, 0x8800, v113
	v_add_u32_e32 v123, 0x9800, v113
	ds_read2_b64 v[166:169], v122 offset0:96 offset1:98
	ds_read2_b64 v[170:173], v123 offset0:128 offset1:130
	ds_read2_b64 v[174:177], v122 offset0:100 offset1:102
	ds_read2_b64 v[178:181], v123 offset0:132 offset1:134
	ds_read2_b64 v[182:185], v122 offset0:104 offset1:106
	ds_read2_b64 v[186:189], v123 offset0:136 offset1:138
	ds_read2_b64 v[190:193], v122 offset0:108 offset1:110
	ds_read2_b64 v[194:197], v123 offset0:140 offset1:142
	v_sub_f32_e32 v206, v206, v114
	v_sub_f32_e32 v207, v207, v114
	v_sub_f32_e32 v208, v208, v114
	v_sub_f32_e32 v209, v209, v114
	v_sub_f32_e32 v210, v210, v114
	v_sub_f32_e32 v211, v211, v114
	v_sub_f32_e32 v212, v212, v114
	v_sub_f32_e32 v213, v213, v114
	v_exp_f32_e32 v206, v206
	v_exp_f32_e32 v207, v207
	v_exp_f32_e32 v208, v208
	v_exp_f32_e32 v209, v209
	v_exp_f32_e32 v210, v210
	v_exp_f32_e32 v211, v211
	v_exp_f32_e32 v212, v212
	v_exp_f32_e32 v213, v213
	v_cvt_pk_bf16_f32 v118, v206, v207
	v_cvt_pk_bf16_f32 v119, v208, v209
	v_cvt_pk_bf16_f32 v120, v210, v211
	v_cvt_pk_bf16_f32 v121, v212, v213
	v_add_f32_e32 v116, v206, v208
	v_add_f32_e32 v117, v207, v209
	v_add_f32_e32 v116, v116, v210
	v_add_f32_e32 v117, v117, v211
	v_add_f32_e32 v116, v116, v212
	v_add_f32_e32 v117, v117, v213
	s_waitcnt lgkmcnt(0)
	v_mfma_f32_32x32x16_bf16 v[18:33], v[166:169], v[118:121], v[18:33]
	v_mfma_f32_32x32x16_bf16 v[2:17], v[170:173], v[118:121], v[2:17]
	v_sub_f32_e32 v214, v214, v114
	v_sub_f32_e32 v215, v215, v114
	v_sub_f32_e32 v216, v216, v114
	v_sub_f32_e32 v217, v217, v114
	v_sub_f32_e32 v218, v218, v114
	v_sub_f32_e32 v219, v219, v114
	v_sub_f32_e32 v220, v220, v114
	v_sub_f32_e32 v221, v221, v114
	v_exp_f32_e32 v214, v214
	v_exp_f32_e32 v215, v215
	v_exp_f32_e32 v216, v216
	v_exp_f32_e32 v217, v217
	v_exp_f32_e32 v218, v218
	v_exp_f32_e32 v219, v219
	v_exp_f32_e32 v220, v220
	v_exp_f32_e32 v221, v221
	v_cvt_pk_bf16_f32 v118, v214, v215
	v_cvt_pk_bf16_f32 v119, v216, v217
	v_cvt_pk_bf16_f32 v120, v218, v219
	v_cvt_pk_bf16_f32 v121, v220, v221
	v_add_f32_e32 v116, v116, v214
	v_add_f32_e32 v117, v117, v215
	v_add_f32_e32 v116, v116, v216
	v_add_f32_e32 v117, v117, v217
	v_add_f32_e32 v116, v116, v218
	v_add_f32_e32 v117, v117, v219
	v_add_f32_e32 v116, v116, v220
	v_add_f32_e32 v117, v117, v221
	v_mfma_f32_32x32x16_bf16 v[18:33], v[174:177], v[118:121], v[18:33]
	v_mfma_f32_32x32x16_bf16 v[2:17], v[178:181], v[118:121], v[2:17]
	v_sub_f32_e32 v222, v222, v114
	v_sub_f32_e32 v223, v223, v114
	v_sub_f32_e32 v224, v224, v114
	v_sub_f32_e32 v225, v225, v114
	v_sub_f32_e32 v226, v226, v114
	v_sub_f32_e32 v227, v227, v114
	v_sub_f32_e32 v228, v228, v114
	v_sub_f32_e32 v229, v229, v114
	v_exp_f32_e32 v222, v222
	v_exp_f32_e32 v223, v223
	v_exp_f32_e32 v224, v224
	v_exp_f32_e32 v225, v225
	v_exp_f32_e32 v226, v226
	v_exp_f32_e32 v227, v227
	v_exp_f32_e32 v228, v228
	v_exp_f32_e32 v229, v229
	v_cvt_pk_bf16_f32 v118, v222, v223
	v_cvt_pk_bf16_f32 v119, v224, v225
	v_cvt_pk_bf16_f32 v120, v226, v227
	v_cvt_pk_bf16_f32 v121, v228, v229
	v_add_f32_e32 v116, v116, v222
	v_add_f32_e32 v117, v117, v223
	v_add_f32_e32 v116, v116, v224
	v_add_f32_e32 v117, v117, v225
	v_add_f32_e32 v116, v116, v226
	v_add_f32_e32 v117, v117, v227
	v_add_f32_e32 v116, v116, v228
	v_add_f32_e32 v117, v117, v229
	v_mfma_f32_32x32x16_bf16 v[18:33], v[182:185], v[118:121], v[18:33]
	v_mfma_f32_32x32x16_bf16 v[2:17], v[186:189], v[118:121], v[2:17]
	v_sub_f32_e32 v230, v230, v114
	v_sub_f32_e32 v231, v231, v114
	v_sub_f32_e32 v232, v232, v114
	v_sub_f32_e32 v233, v233, v114
	v_sub_f32_e32 v234, v234, v114
	v_sub_f32_e32 v235, v235, v114
	v_sub_f32_e32 v236, v236, v114
	v_sub_f32_e32 v237, v237, v114
	v_exp_f32_e32 v230, v230
	v_exp_f32_e32 v231, v231
	v_exp_f32_e32 v232, v232
	v_exp_f32_e32 v233, v233
	v_exp_f32_e32 v234, v234
	v_exp_f32_e32 v235, v235
	v_exp_f32_e32 v236, v236
	v_exp_f32_e32 v237, v237
	v_cvt_pk_bf16_f32 v118, v230, v231
	v_cvt_pk_bf16_f32 v119, v232, v233
	v_cvt_pk_bf16_f32 v120, v234, v235
	v_cvt_pk_bf16_f32 v121, v236, v237
	v_add_f32_e32 v116, v116, v230
	v_add_f32_e32 v117, v117, v231
	v_add_f32_e32 v116, v116, v232
	v_add_f32_e32 v117, v117, v233
	v_add_f32_e32 v116, v116, v234
	v_add_f32_e32 v117, v117, v235
	v_add_f32_e32 v116, v116, v236
	v_add_f32_e32 v117, v117, v237
	v_mfma_f32_32x32x16_bf16 v[18:33], v[190:193], v[118:121], v[18:33]
	v_mfma_f32_32x32x16_bf16 v[2:17], v[194:197], v[118:121], v[2:17]
	v_add_f32_e32 v116, v116, v117
	v_add_f32_e32 v109, v109, v116
; __device__ __forceinline__ void attn_tile(int t, int buf, LAS unsigned char* lds, const bf16x8 (&qr)[4], float cq2, int qlo, int qpos, int q32, int hi,
;                                           float& mrun, float& lrun, f32x16& o0, f32x16& o1) {
;     ...
;     f32x2 ls2 = (f32x2){0.f, 0.f};
; #pragma unroll
;     for (int r = 0; r < 16; r += 2) {
;         const f32x2 d0 = (f32x2){s0[r], s0[r + 1]} - mnew, d1 = (f32x2){s1[r], s1[r + 1]} - mnew;
;         f32x2 e0, e1; e0.x = fexp2(d0.x); e0.y = fexp2(d0.y); e1.x = fexp2(d1.x); e1.y = fexp2(d1.y);
;         s0[r] = e0.x; s0[r + 1] = e0.y; s1[r] = e1.x; s1[r + 1] = e1.y;
;         ls2 += e0 + e1;
;     }
;     lrun += ls2.x + ls2.y;
; #pragma unroll
;     for (int p = 0; p < 2; ++p)
; #pragma unroll
;         for (int sx = 0; sx < 2; ++sx) {
;             u32x4 pw;
;             if (p == 0) pw = (u32x4){pk_bf16(s0[8 * sx + 0], s0[8 * sx + 1]), pk_bf16(s0[8 * sx + 2], s0[8 * sx + 3]), pk_bf16(s0[8 * sx + 4], s0[8 * sx + 5]), pk_bf16(s0[8 * sx + 6], s0[8 * sx + 7])};
;             else        pw = (u32x4){pk_bf16(s1[8 * sx + 0], s1[8 * sx + 1]), pk_bf16(s1[8 * sx + 2], s1[8 * sx + 3]), pk_bf16(s1[8 * sx + 4], s1[8 * sx + 5]), pk_bf16(s1[8 * sx + 6], s1[8 * sx + 7])};
;             const bf16x8 pf = __builtin_bit_cast(bf16x8, pw);
;             const int ko = (32 * p + 16 * sx + 4 * hi) * 2;
;             const u32x2 a0 = *(const LAS u32x2*)(Vt + q32 * 136 + ko), a1 = *(const LAS u32x2*)(Vt + q32 * 136 + ko + 16);
;             const u32x2 b0 = *(const LAS u32x2*)(Vt + (32 + q32) * 136 + ko), b1 = *(const LAS u32x2*)(Vt + (32 + q32) * 136 + ko + 16);
;             const bf16x8 vf0 = __builtin_bit_cast(bf16x8, (u32x4){a0.x, a0.y, a1.x, a1.y});
; __device__ __forceinline__ void attn_unit(const AttnJob& J, LAS unsigned char* lds) {
;     ...
;     for (int t = 0; t < J.NT; t += 2) {
;         attn_stage(lds, 0, kA, vA);
;         __syncthreads();
;         if (t + 2 < J.NT) attn_load(J, t + 2, kA, vA);
;         if (active && 64 * t <= qlo + 31) attn_tile(t, 0, lds, qr, cq2, qlo, qpos, q32, hi, mrun, lrun, o0, o1);
;         if (t + 1 < J.NT) {
;             attn_stage(lds, 1, kB, vB);
;             __syncthreads();
;             if (t + 3 < J.NT) attn_load(J, t + 3, kB, vB);
;             if (active && 64 * (t + 1) <= qlo + 31) attn_tile(t + 1, 1, lds, qr, cq2, qlo, qpos, q32, hi, mrun, lrun, o0, o1);
;         }
;     }
.Lend_E:
.Lslot_O:
	s_waitcnt vmcnt(2)
	ds_write_b128 v156, v[90:93] offset:17664
	ds_write_b16 v157, v86 offset:26880
	ds_write_b16_d16_hi v157, v86 offset:27016
	ds_write_b16 v157, v87 offset:27152
	ds_write_b16_d16_hi v157, v87 offset:27288
	ds_write_b16 v157, v88 offset:27424
	ds_write_b16_d16_hi v157, v88 offset:27560
	ds_write_b16 v157, v89 offset:27696
	ds_write_b16_d16_hi v157, v89 offset:27832
	s_waitcnt lgkmcnt(0)
	s_barrier
	s_add_i32 s6, s22, 3
	s_lshl_b32 s6, s6, 18
	s_add_u32 s98, s8, s6
	s_addc_u32 s99, s9, 0
	global_load_dwordx4 v[90:93], v158, s[98:99] offset:1024
	s_sub_u32 s100, s98, 0x40000
	s_subb_u32 s101, s99, 0
	global_load_dwordx4 v[86:89], v158, s[100:101] offset:2048
	s_lshl_b32 s6, s22, 6
	s_add_i32 s6, s6, 64
	s_cmp_le_i32 s6, s23
	s_cbranch_scc0 .Lnoproc_O
	ds_read_b128 v[124:127], v112 offset:17664
	ds_read_b128 v[206:209], v111 offset:256
	ds_read_b128 v[210:213], v111 offset:288
	ds_read_b128 v[214:217], v111 offset:320
	ds_read_b128 v[218:221], v111 offset:352
	ds_read_b128 v[128:131], v112 offset:22272
	ds_read_b128 v[222:225], v111 offset:384
	ds_read_b128 v[226:229], v111 offset:416
	ds_read_b128 v[230:233], v111 offset:448
	ds_read_b128 v[234:237], v111 offset:480
	ds_read_b128 v[132:135], v112 offset:17696
	ds_read_b128 v[136:139], v112 offset:22304
	ds_read_b128 v[140:143], v112 offset:17728
	ds_read_b128 v[144:147], v112 offset:22336
	s_cmp_eq_u32 s26, 0
	s_cbranch_scc1 .Lqkonly_O
	v_sub_f32_e32 v34, v34, v114
	v_sub_f32_e32 v35, v35, v114
	v_sub_f32_e32 v36, v36, v114
	v_sub_f32_e32 v37, v37, v114
	v_sub_f32_e32 v38, v38, v114
	v_sub_f32_e32 v39, v39, v114
	v_sub_f32_e32 v40, v40, v114
	v_sub_f32_e32 v41, v41, v114
	v_exp_f32_e32 v34, v34
	v_exp_f32_e32 v35, v35
	v_exp_f32_e32 v36, v36
	v_exp_f32_e32 v37, v37
	v_exp_f32_e32 v38, v38
	v_exp_f32_e32 v39, v39
	v_exp_f32_e32 v40, v40
	v_exp_f32_e32 v41, v41
	v_cvt_pk_bf16_f32 v118, v34, v35
	v_cvt_pk_bf16_f32 v119, v36, v37
	v_cvt_pk_bf16_f32 v120, v38, v39
	v_cvt_pk_bf16_f32 v121, v40, v41
	v_add_f32_e32 v116, v34, v36
	v_add_f32_e32 v117, v35, v37
	v_add_f32_e32 v116, v116, v38
	v_add_f32_e32 v117, v117, v39
	v_add_f32_e32 v116, v116, v40
	v_add_f32_e32 v117, v117, v41
	s_waitcnt lgkmcnt(9)
	v_mfma_f32_32x32x16_bf16 v[206:221], v[124:127], v[78:81], v[206:221]
	ds_read_b128 v[148:151], v112 offset:17760
	ds_read_b128 v[152:155], v112 offset:22368
	s_waitcnt lgkmcnt(6)
	v_mfma_f32_32x32x16_bf16 v[222:237], v[128:131], v[78:81], v[222:237]
	s_waitcnt lgkmcnt(5)
	v_mfma_f32_32x32x16_bf16 v[206:221], v[132:135], v[74:77], v[206:221]
	s_waitcnt lgkmcnt(4)
	v_mfma_f32_32x32x16_bf16 v[222:237], v[136:139], v[74:77], v[222:237]
	s_waitcnt lgkmcnt(3)
	v_mfma_f32_32x32x16_bf16 v[206:221], v[140:143], v[70:73], v[206:221]
	s_waitcnt lgkmcnt(2)
	v_mfma_f32_32x32x16_bf16 v[222:237], v[144:147], v[70:73], v[222:237]
	s_waitcnt lgkmcnt(1)
	v_mfma_f32_32x32x16_bf16 v[206:221], v[148:151], v[66:69], v[206:221]
	s_waitcnt lgkmcnt(0)
	v_mfma_f32_32x32x16_bf16 v[222:237], v[152:155], v[66:69], v[222:237]
	v_add_u32_e32 v122, 0x6800, v113
	v_add_u32_e32 v123, 0x7800, v113
	ds_read2_b64 v[166:169], v122 offset0:32 offset1:34
	ds_read2_b64 v[170:173], v123 offset0:64 offset1:66
	ds_read2_b64 v[174:177], v122 offset0:36 offset1:38
	ds_read2_b64 v[178:181], v123 offset0:68 offset1:70
	ds_read2_b64 v[182:185], v122 offset0:40 offset1:42
	ds_read2_b64 v[186:189], v123 offset0:72 offset1:74
	ds_read2_b64 v[190:193], v122 offset0:44 offset1:46
	ds_read2_b64 v[194:197], v123 offset0:76 offset1:78
	v_sub_f32_e32 v42, v42, v114
	v_sub_f32_e32 v43, v43, v114
	v_sub_f32_e32 v44, v44, v114
	v_sub_f32_e32 v45, v45, v114
	v_sub_f32_e32 v46, v46, v114
	v_sub_f32_e32 v47, v47, v114
	v_sub_f32_e32 v48, v48, v114
	v_sub_f32_e32 v49, v49, v114
	v_exp_f32_e32 v42, v42
	v_exp_f32_e32 v43, v43
	v_exp_f32_e32 v44, v44
	v_exp_f32_e32 v45, v45
	v_exp_f32_e32 v46, v46
	v_exp_f32_e32 v47, v47
	v_exp_f32_e32 v48, v48
	v_exp_f32_e32 v49, v49
	s_waitcnt lgkmcnt(0)
	v_mfma_f32_32x32x16_bf16 v[18:33], v[166:169], v[118:121], v[18:33]
	v_mfma_f32_32x32x16_bf16 v[2:17], v[170:173], v[118:121], v[2:17]
	v_cvt_pk_bf16_f32 v118, v42, v43
	v_cvt_pk_bf16_f32 v119, v44, v45
	v_cvt_pk_bf16_f32 v120, v46, v47
	v_cvt_pk_bf16_f32 v121, v48, v49
	v_add_f32_e32 v116, v116, v42
	v_add_f32_e32 v117, v117, v43
	v_add_f32_e32 v116, v116, v44
	v_add_f32_e32 v117, v117, v45
	v_add_f32_e32 v116, v116, v46
	v_add_f32_e32 v117, v117, v47
	v_add_f32_e32 v116, v116, v48
	v_add_f32_e32 v117, v117, v49
	v_mfma_f32_32x32x16_bf16 v[18:33], v[174:177], v[118:121], v[18:33]
	v_mfma_f32_32x32x16_bf16 v[2:17], v[178:181], v[118:121], v[2:17]
	v_sub_f32_e32 v50, v50, v114
	v_sub_f32_e32 v51, v51, v114
	v_sub_f32_e32 v52, v52, v114
	v_sub_f32_e32 v53, v53, v114
	v_sub_f32_e32 v54, v54, v114
	v_sub_f32_e32 v55, v55, v114
	v_sub_f32_e32 v56, v56, v114
	v_sub_f32_e32 v57, v57, v114
	v_exp_f32_e32 v50, v50
	v_exp_f32_e32 v51, v51
	v_exp_f32_e32 v52, v52
	v_exp_f32_e32 v53, v53
	v_exp_f32_e32 v54, v54
	v_exp_f32_e32 v55, v55
	v_exp_f32_e32 v56, v56
	v_exp_f32_e32 v57, v57
	v_cvt_pk_bf16_f32 v118, v50, v51
	v_cvt_pk_bf16_f32 v119, v52, v53
	v_cvt_pk_bf16_f32 v120, v54, v55
	v_cvt_pk_bf16_f32 v121, v56, v57
	v_add_f32_e32 v116, v116, v50
	v_add_f32_e32 v117, v117, v51
	v_add_f32_e32 v116, v116, v52
	v_add_f32_e32 v117, v117, v53
	v_add_f32_e32 v116, v116, v54
	v_add_f32_e32 v117, v117, v55
	v_add_f32_e32 v116, v116, v56
	v_add_f32_e32 v117, v117, v57
	v_mfma_f32_32x32x16_bf16 v[18:33], v[182:185], v[118:121], v[18:33]
	v_mfma_f32_32x32x16_bf16 v[2:17], v[186:189], v[118:121], v[2:17]
	v_sub_f32_e32 v58, v58, v114
	v_sub_f32_e32 v59, v59, v114
	v_sub_f32_e32 v60, v60, v114
	v_sub_f32_e32 v61, v61, v114
	v_sub_f32_e32 v62, v62, v114
	v_sub_f32_e32 v63, v63, v114
	v_sub_f32_e32 v64, v64, v114
	v_sub_f32_e32 v65, v65, v114
	v_exp_f32_e32 v58, v58
	v_exp_f32_e32 v59, v59
	v_exp_f32_e32 v60, v60
	v_exp_f32_e32 v61, v61
	v_exp_f32_e32 v62, v62
	v_exp_f32_e32 v63, v63
	v_exp_f32_e32 v64, v64
	v_exp_f32_e32 v65, v65
	v_cvt_pk_bf16_f32 v118, v58, v59
	v_cvt_pk_bf16_f32 v119, v60, v61
	v_cvt_pk_bf16_f32 v120, v62, v63
	v_cvt_pk_bf16_f32 v121, v64, v65
	v_add_f32_e32 v116, v116, v58
	v_add_f32_e32 v117, v117, v59
	v_add_f32_e32 v116, v116, v60
	v_add_f32_e32 v117, v117, v61
	v_add_f32_e32 v116, v116, v62
	v_add_f32_e32 v117, v117, v63
	v_add_f32_e32 v116, v116, v64
	v_add_f32_e32 v117, v117, v65
	v_mfma_f32_32x32x16_bf16 v[18:33], v[190:193], v[118:121], v[18:33]
	v_mfma_f32_32x32x16_bf16 v[2:17], v[194:197], v[118:121], v[2:17]
	v_add_f32_e32 v116, v116, v117
	v_add_f32_e32 v109, v109, v116
	s_branch .Lmax_O

; __device__ __forceinline__ float fexp2(float x) { return __builtin_amdgcn_exp2f(x); }
; __device__ __forceinline__ void attn_tile(int t, int buf, LAS unsigned char* lds, const bf16x8 (&qr)[4], float cq2, int qlo, int qpos, int q32, int hi,
;                                           float& mrun, float& lrun, f32x16& o0, f32x16& o1) {
;     ...
;     float mx = fmaxf(s0[0], s1[0]);
; #pragma unroll
;     for (int r = 1; r < 16; ++r) mx = fmaxf(mx, fmaxf(s0[r], s1[r]));
;     mx = fmaxf(mx, __shfl_xor(mx, 32));
;     const float mnew = fmaxf(mrun, mx);
;     if (__any(mnew > mrun)) {
;         const float alpha = fexp2(mrun - mnew); lrun *= alpha;
; #pragma unroll
;         for (int r = 0; r < 16; ++r) { o0[r] *= alpha; o1[r] *= alpha; }
;     }
;     mrun = mnew;
.Lnomask_O:
	v_max3_f32 v0, v206, v222, v207
	v_max3_f32 v115, v223, v208, v224
	v_max3_f32 v0, v0, v209, v225
	v_max3_f32 v115, v115, v210, v226
	v_max3_f32 v0, v0, v211, v227
	v_max3_f32 v115, v115, v212, v228
	v_max3_f32 v0, v0, v213, v229
	v_max3_f32 v115, v115, v214, v230
	v_max3_f32 v0, v0, v215, v231
	v_max3_f32 v115, v115, v216, v232
	v_max3_f32 v0, v0, v217, v233
	v_max3_f32 v115, v115, v218, v234
	v_max3_f32 v0, v0, v219, v235
	v_max3_f32 v115, v115, v220, v236
	v_max3_f32 v0, v0, v221, v237
	v_max_f32_e32 v0, v0, v115
	ds_bpermute_b32 v115, v107, v0
	s_waitcnt lgkmcnt(0)
	v_max3_f32 v0, v114, v0, v115
	v_add_f32_e32 v115, 0x41c00000, v114
	v_cmp_gt_f32_e32 vcc, v0, v115
	s_cbranch_vccz .Lnoresc_O
	v_sub_f32_e32 v114, v114, v0
	v_exp_f32_e32 v114, v114
	s_nop 0
	v_mul_f32_e32 v109, v109, v114
	v_mul_f32_e32 v33, v33, v114
	v_mul_f32_e32 v32, v32, v114
	v_mul_f32_e32 v31, v31, v114
	v_mul_f32_e32 v30, v30, v114
	v_mul_f32_e32 v29, v29, v114
	v_mul_f32_e32 v28, v28, v114
	v_mul_f32_e32 v27, v27, v114
	v_mul_f32_e32 v26, v26, v114
	v_mul_f32_e32 v25, v25, v114
	v_mul_f32_e32 v24, v24, v114
	v_mul_f32_e32 v23, v23, v114
	v_mul_f32_e32 v22, v22, v114
	v_mul_f32_e32 v21, v21, v114
	v_mul_f32_e32 v20, v20, v114
	v_mul_f32_e32 v19, v19, v114
	v_mul_f32_e32 v18, v18, v114
	v_mul_f32_e32 v17, v17, v114
	v_mul_f32_e32 v16, v16, v114
	v_mul_f32_e32 v15, v15, v114
	v_mul_f32_e32 v14, v14, v114
	v_mul_f32_e32 v13, v13, v114
	v_mul_f32_e32 v12, v12, v114
	v_mul_f32_e32 v11, v11, v114
	v_mul_f32_e32 v10, v10, v114
	v_mul_f32_e32 v9, v9, v114
	v_mul_f32_e32 v8, v8, v114
	v_mul_f32_e32 v7, v7, v114
	v_mul_f32_e32 v6, v6, v114
	v_mul_f32_e32 v5, v5, v114
	v_mul_f32_e32 v4, v4, v114
	v_mul_f32_e32 v3, v3, v114
	v_mul_f32_e32 v2, v2, v114
	v_mov_b32_e32 v114, v0

; #define LAS __attribute__((address_space(3)))
; __device__ __forceinline__ unsigned pk_bf16(float lo, float hi) { const f32x2_t v = {lo, hi}; const bf16x2_t b = __builtin_convertvector(v, bf16x2_t); return __builtin_bit_cast(unsigned, b); }
; __device__ __forceinline__ float fexp2(float x) { return __builtin_amdgcn_exp2f(x); }
; __device__ __forceinline__ void attn_tile(int t, int buf, LAS unsigned char* lds, const bf16x8 (&qr)[4], float cq2, int qlo, int qpos, int q32, int hi,
;                                           float& mrun, float& lrun, f32x16& o0, f32x16& o1) {
;     ...
;     f32x2 ls2 = (f32x2){0.f, 0.f};
; #pragma unroll
;     for (int r = 0; r < 16; r += 2) {
;         const f32x2 d0 = (f32x2){s0[r], s0[r + 1]} - mnew, d1 = (f32x2){s1[r], s1[r + 1]} - mnew;
;         f32x2 e0, e1; e0.x = fexp2(d0.x); e0.y = fexp2(d0.y); e1.x = fexp2(d1.x); e1.y = fexp2(d1.y);
;         s0[r] = e0.x; s0[r + 1] = e0.y; s1[r] = e1.x; s1[r + 1] = e1.y;
;         ls2 += e0 + e1;
;     }
;     lrun += ls2.x + ls2.y;
; #pragma unroll
;     for (int p = 0; p < 2; ++p)
; #pragma unroll
;         for (int sx = 0; sx < 2; ++sx) {
;             u32x4 pw;
;             if (p == 0) pw = (u32x4){pk_bf16(s0[8 * sx + 0], s0[8 * sx + 1]), pk_bf16(s0[8 * sx + 2], s0[8 * sx + 3]), pk_bf16(s0[8 * sx + 4], s0[8 * sx + 5]), pk_bf16(s0[8 * sx + 6], s0[8 * sx + 7])};
;             else        pw = (u32x4){pk_bf16(s1[8 * sx + 0], s1[8 * sx + 1]), pk_bf16(s1[8 * sx + 2], s1[8 * sx + 3]), pk_bf16(s1[8 * sx + 4], s1[8 * sx + 5]), pk_bf16(s1[8 * sx + 6], s1[8 * sx + 7])};
;             const bf16x8 pf = __builtin_bit_cast(bf16x8, pw);
;             const int ko = (32 * p + 16 * sx + 4 * hi) * 2;
;             const u32x2 a0 = *(const LAS u32x2*)(Vt + q32 * 136 + ko), a1 = *(const LAS u32x2*)(Vt + q32 * 136 + ko + 16);
;             const u32x2 b0 = *(const LAS u32x2*)(Vt + (32 + q32) * 136 + ko), b1 = *(const LAS u32x2*)(Vt + (32 + q32) * 136 + ko + 16);
;             const bf16x8 vf0 = __builtin_bit_cast(bf16x8, (u32x4){a0.x, a0.y, a1.x, a1.y});
;             const bf16x8 vf1 = __builtin_bit_cast(bf16x8, (u32x4){b0.x, b0.y, b1.x, b1.y});
;             o0 = __builtin_amdgcn_mfma_f32_32x32x16_bf16(vf0, pf, o0, 0, 0, 0);
;             o1 = __builtin_amdgcn_mfma_f32_32x32x16_bf16(vf1, pf, o1, 0, 0, 0);
;         }
.Lnoproc_O:
	s_mov_b32 s27, 0
	s_cmp_eq_u32 s26, 0
	s_cbranch_scc1 .Lend_O
	v_add_u32_e32 v122, 0x6800, v113
	v_add_u32_e32 v123, 0x7800, v113
	ds_read2_b64 v[166:169], v122 offset0:32 offset1:34
	ds_read2_b64 v[170:173], v123 offset0:64 offset1:66
	ds_read2_b64 v[174:177], v122 offset0:36 offset1:38
	ds_read2_b64 v[178:181], v123 offset0:68 offset1:70
	ds_read2_b64 v[182:185], v122 offset0:40 offset1:42
	ds_read2_b64 v[186:189], v123 offset0:72 offset1:74
	ds_read2_b64 v[190:193], v122 offset0:44 offset1:46
	ds_read2_b64 v[194:197], v123 offset0:76 offset1:78
	v_sub_f32_e32 v34, v34, v114
	v_sub_f32_e32 v35, v35, v114
	v_sub_f32_e32 v36, v36, v114
	v_sub_f32_e32 v37, v37, v114
	v_sub_f32_e32 v38, v38, v114
	v_sub_f32_e32 v39, v39, v114
	v_sub_f32_e32 v40, v40, v114
	v_sub_f32_e32 v41, v41, v114
	v_exp_f32_e32 v34, v34
	v_exp_f32_e32 v35, v35
	v_exp_f32_e32 v36, v36
	v_exp_f32_e32 v37, v37
	v_exp_f32_e32 v38, v38
	v_exp_f32_e32 v39, v39
	v_exp_f32_e32 v40, v40
	v_exp_f32_e32 v41, v41
	v_cvt_pk_bf16_f32 v118, v34, v35
	v_cvt_pk_bf16_f32 v119, v36, v37
	v_cvt_pk_bf16_f32 v120, v38, v39
	v_cvt_pk_bf16_f32 v121, v40, v41
	v_add_f32_e32 v116, v34, v36
	v_add_f32_e32 v117, v35, v37
	v_add_f32_e32 v116, v116, v38
	v_add_f32_e32 v117, v117, v39
	v_add_f32_e32 v116, v116, v40
	v_add_f32_e32 v117, v117, v41
	s_waitcnt lgkmcnt(0)
	v_mfma_f32_32x32x16_bf16 v[18:33], v[166:169], v[118:121], v[18:33]
	v_mfma_f32_32x32x16_bf16 v[2:17], v[170:173], v[118:121], v[2:17]
	v_sub_f32_e32 v42, v42, v114
	v_sub_f32_e32 v43, v43, v114
	v_sub_f32_e32 v44, v44, v114
	v_sub_f32_e32 v45, v45, v114
	v_sub_f32_e32 v46, v46, v114
	v_sub_f32_e32 v47, v47, v114
	v_sub_f32_e32 v48, v48, v114
	v_sub_f32_e32 v49, v49, v114
	v_exp_f32_e32 v42, v42
	v_exp_f32_e32 v43, v43
	v_exp_f32_e32 v44, v44
	v_exp_f32_e32 v45, v45
	v_exp_f32_e32 v46, v46
	v_exp_f32_e32 v47, v47
	v_exp_f32_e32 v48, v48
	v_exp_f32_e32 v49, v49
	v_cvt_pk_bf16_f32 v118, v42, v43
	v_cvt_pk_bf16_f32 v119, v44, v45
	v_cvt_pk_bf16_f32 v120, v46, v47
	v_cvt_pk_bf16_f32 v121, v48, v49
	v_add_f32_e32 v116, v116, v42
	v_add_f32_e32 v117, v117, v43
	v_add_f32_e32 v116, v116, v44
	v_add_f32_e32 v117, v117, v45
	v_add_f32_e32 v116, v116, v46
	v_add_f32_e32 v117, v117, v47
	v_add_f32_e32 v116, v116, v48
	v_add_f32_e32 v117, v117, v49
	v_mfma_f32_32x32x16_bf16 v[18:33], v[174:177], v[118:121], v[18:33]
	v_mfma_f32_32x32x16_bf16 v[2:17], v[178:181], v[118:121], v[2:17]
	v_sub_f32_e32 v50, v50, v114
	v_sub_f32_e32 v51, v51, v114
	v_sub_f32_e32 v52, v52, v114
	v_sub_f32_e32 v53, v53, v114
	v_sub_f32_e32 v54, v54, v114
	v_sub_f32_e32 v55, v55, v114
	v_sub_f32_e32 v56, v56, v114
	v_sub_f32_e32 v57, v57, v114
	v_exp_f32_e32 v50, v50
	v_exp_f32_e32 v51, v51
	v_exp_f32_e32 v52, v52
	v_exp_f32_e32 v53, v53
	v_exp_f32_e32 v54, v54
	v_exp_f32_e32 v55, v55
	v_exp_f32_e32 v56, v56
	v_exp_f32_e32 v57, v57
	v_cvt_pk_bf16_f32 v118, v50, v51
	v_cvt_pk_bf16_f32 v119, v52, v53
	v_cvt_pk_bf16_f32 v120, v54, v55
	v_cvt_pk_bf16_f32 v121, v56, v57
	v_add_f32_e32 v116, v116, v50
	v_add_f32_e32 v117, v117, v51
	v_add_f32_e32 v116, v116, v52
	v_add_f32_e32 v117, v117, v53
	v_add_f32_e32 v116, v116, v54
	v_add_f32_e32 v117, v117, v55
	v_add_f32_e32 v116, v116, v56
	v_add_f32_e32 v117, v117, v57
	v_mfma_f32_32x32x16_bf16 v[18:33], v[182:185], v[118:121], v[18:33]
	v_mfma_f32_32x32x16_bf16 v[2:17], v[186:189], v[118:121], v[2:17]
	v_sub_f32_e32 v58, v58, v114
	v_sub_f32_e32 v59, v59, v114
	v_sub_f32_e32 v60, v60, v114
	v_sub_f32_e32 v61, v61, v114
	v_sub_f32_e32 v62, v62, v114
	v_sub_f32_e32 v63, v63, v114
	v_sub_f32_e32 v64, v64, v114
	v_sub_f32_e32 v65, v65, v114
	v_exp_f32_e32 v58, v58
	v_exp_f32_e32 v59, v59
	v_exp_f32_e32 v60, v60
	v_exp_f32_e32 v61, v61
	v_exp_f32_e32 v62, v62
	v_exp_f32_e32 v63, v63
	v_exp_f32_e32 v64, v64
	v_exp_f32_e32 v65, v65
	v_cvt_pk_bf16_f32 v118, v58, v59
	v_cvt_pk_bf16_f32 v119, v60, v61
	v_cvt_pk_bf16_f32 v120, v62, v63
	v_cvt_pk_bf16_f32 v121, v64, v65
	v_add_f32_e32 v116, v116, v58
	v_add_f32_e32 v117, v117, v59
	v_add_f32_e32 v116, v116, v60
	v_add_f32_e32 v117, v117, v61
	v_add_f32_e32 v116, v116, v62
	v_add_f32_e32 v117, v117, v63
	v_add_f32_e32 v116, v116, v64
	v_add_f32_e32 v117, v117, v65
	v_mfma_f32_32x32x16_bf16 v[18:33], v[190:193], v[118:121], v[18:33]
	v_mfma_f32_32x32x16_bf16 v[2:17], v[194:197], v[118:121], v[2:17]
	v_add_f32_e32 v116, v116, v117
	v_add_f32_e32 v109, v109, v116
; __device__ __forceinline__ void attn_tile(int t, int buf, LAS unsigned char* lds, const bf16x8 (&qr)[4], float cq2, int qlo, int qpos, int q32, int hi,
;                                           float& mrun, float& lrun, f32x16& o0, f32x16& o1) {
;     ...
;     f32x2 ls2 = (f32x2){0.f, 0.f};
; #pragma unroll
;     for (int r = 0; r < 16; r += 2) {
;         const f32x2 d0 = (f32x2){s0[r], s0[r + 1]} - mnew, d1 = (f32x2){s1[r], s1[r + 1]} - mnew;
;         f32x2 e0, e1; e0.x = fexp2(d0.x); e0.y = fexp2(d0.y); e1.x = fexp2(d1.x); e1.y = fexp2(d1.y);
;         s0[r] = e0.x; s0[r + 1] = e0.y; s1[r] = e1.x; s1[r + 1] = e1.y;
;         ls2 += e0 + e1;
;     }
;     lrun += ls2.x + ls2.y;
; #pragma unroll
;     for (int p = 0; p < 2; ++p)
; #pragma unroll
;         for (int sx = 0; sx < 2; ++sx) {
;             u32x4 pw;
;             if (p == 0) pw = (u32x4){pk_bf16(s0[8 * sx + 0], s0[8 * sx + 1]), pk_bf16(s0[8 * sx + 2], s0[8 * sx + 3]), pk_bf16(s0[8 * sx + 4], s0[8 * sx + 5]), pk_bf16(s0[8 * sx + 6], s0[8 * sx + 7])};
;             else        pw = (u32x4){pk_bf16(s1[8 * sx + 0], s1[8 * sx + 1]), pk_bf16(s1[8 * sx + 2], s1[8 * sx + 3]), pk_bf16(s1[8 * sx + 4], s1[8 * sx + 5]), pk_bf16(s1[8 * sx + 6], s1[8 * sx + 7])};
;             const bf16x8 pf = __builtin_bit_cast(bf16x8, pw);
;             const int ko = (32 * p + 16 * sx + 4 * hi) * 2;
;             const u32x2 a0 = *(const LAS u32x2*)(Vt + q32 * 136 + ko), a1 = *(const LAS u32x2*)(Vt + q32 * 136 + ko + 16);
;             const u32x2 b0 = *(const LAS u32x2*)(Vt + (32 + q32) * 136 + ko), b1 = *(const LAS u32x2*)(Vt + (32 + q32) * 136 + ko + 16);
;             const bf16x8 vf0 = __builtin_bit_cast(bf16x8, (u32x4){a0.x, a0.y, a1.x, a1.y});
; __device__ __forceinline__ void attn_unit(const AttnJob& J, LAS unsigned char* lds) {
;     ...
;     for (int t = 0; t < J.NT; t += 2) {
;         attn_stage(lds, 0, kA, vA);
;         __syncthreads();
;         if (t + 2 < J.NT) attn_load(J, t + 2, kA, vA);
;         if (active && 64 * t <= qlo + 31) attn_tile(t, 0, lds, qr, cq2, qlo, qpos, q32, hi, mrun, lrun, o0, o1);
;         if (t + 1 < J.NT) {
;             attn_stage(lds, 1, kB, vB);
;             __syncthreads();
;             if (t + 3 < J.NT) attn_load(J, t + 3, kB, vB);
;             if (active && 64 * (t + 1) <= qlo + 31) attn_tile(t + 1, 1, lds, qr, cq2, qlo, qpos, q32, hi, mrun, lrun, o0, o1);
;         }
;     }
.Lend_O:
	s_add_i32 s22, s22, 2
	v_add_u32_e32 v111, 0x200, v111
	s_cmp_lt_u32 s22, s20
	s_cbranch_scc1 .Lslot_E
	s_waitcnt vmcnt(0)
	ds_write_b16 v157, v94 offset:35584
	ds_write_b16_d16_hi v157, v94 offset:35720
	ds_write_b16 v157, v95 offset:35856
	ds_write_b16_d16_hi v157, v95 offset:35992
	ds_write_b16 v157, v96 offset:36128
	ds_write_b16_d16_hi v157, v96 offset:36264
	ds_write_b16 v157, v97 offset:36400
	ds_write_b16_d16_hi v157, v97 offset:36536
	s_waitcnt lgkmcnt(0)
	s_barrier
	s_cmp_eq_u32 s27, 0
	s_cbranch_scc1 .LBB0_663
	v_add_u32_e32 v122, 0x8800, v113
	v_add_u32_e32 v123, 0x9800, v113
	ds_read2_b64 v[166:169], v122 offset0:96 offset1:98
	ds_read2_b64 v[170:173], v123 offset0:128 offset1:130
	ds_read2_b64 v[174:177], v122 offset0:100 offset1:102
	ds_read2_b64 v[178:181], v123 offset0:132 offset1:134
	ds_read2_b64 v[182:185], v122 offset0:104 offset1:106
	ds_read2_b64 v[186:189], v123 offset0:136 offset1:138
	ds_read2_b64 v[190:193], v122 offset0:108 offset1:110
	ds_read2_b64 v[194:197], v123 offset0:140 offset1:142
	v_sub_f32_e32 v206, v206, v114
	v_sub_f32_e32 v207, v207, v114
	v_sub_f32_e32 v208, v208, v114
	v_sub_f32_e32 v209, v209, v114
	v_sub_f32_e32 v210, v210, v114
	v_sub_f32_e32 v211, v211, v114
	v_sub_f32_e32 v212, v212, v114
	v_sub_f32_e32 v213, v213, v114
	v_exp_f32_e32 v206, v206
	v_exp_f32_e32 v207, v207
	v_exp_f32_e32 v208, v208
	v_exp_f32_e32 v209, v209
	v_exp_f32_e32 v210, v210
	v_exp_f32_e32 v211, v211
	v_exp_f32_e32 v212, v212
	v_exp_f32_e32 v213, v213
	v_cvt_pk_bf16_f32 v118, v206, v207
	v_cvt_pk_bf16_f32 v119, v208, v209
	v_cvt_pk_bf16_f32 v120, v210, v211
	v_cvt_pk_bf16_f32 v121, v212, v213
	v_add_f32_e32 v116, v206, v208
	v_add_f32_e32 v117, v207, v209
	v_add_f32_e32 v116, v116, v210
	v_add_f32_e32 v117, v117, v211
	v_add_f32_e32 v116, v116, v212
	v_add_f32_e32 v117, v117, v213
	s_waitcnt lgkmcnt(0)
	v_mfma_f32_32x32x16_bf16 v[18:33], v[166:169], v[118:121], v[18:33]
	v_mfma_f32_32x32x16_bf16 v[2:17], v[170:173], v[118:121], v[2:17]
	v_sub_f32_e32 v214, v214, v114
	v_sub_f32_e32 v215, v215, v114
	v_sub_f32_e32 v216, v216, v114
	v_sub_f32_e32 v217, v217, v114
	v_sub_f32_e32 v218, v218, v114
	v_sub_f32_e32 v219, v219, v114
	v_sub_f32_e32 v220, v220, v114
	v_sub_f32_e32 v221, v221, v114
	v_exp_f32_e32 v214, v214
	v_exp_f32_e32 v215, v215
	v_exp_f32_e32 v216, v216
	v_exp_f32_e32 v217, v217
	v_exp_f32_e32 v218, v218
	v_exp_f32_e32 v219, v219
	v_exp_f32_e32 v220, v220
	v_exp_f32_e32 v221, v221
	v_cvt_pk_bf16_f32 v118, v214, v215
	v_cvt_pk_bf16_f32 v119, v216, v217
	v_cvt_pk_bf16_f32 v120, v218, v219
	v_cvt_pk_bf16_f32 v121, v220, v221
	v_add_f32_e32 v116, v116, v214
	v_add_f32_e32 v117, v117, v215
	v_add_f32_e32 v116, v116, v216
	v_add_f32_e32 v117, v117, v217
	v_add_f32_e32 v116, v116, v218
	v_add_f32_e32 v117, v117, v219
	v_add_f32_e32 v116, v116, v220
	v_add_f32_e32 v117, v117, v221
	v_mfma_f32_32x32x16_bf16 v[18:33], v[174:177], v[118:121], v[18:33]
	v_mfma_f32_32x32x16_bf16 v[2:17], v[178:181], v[118:121], v[2:17]
	v_sub_f32_e32 v222, v222, v114
	v_sub_f32_e32 v223, v223, v114
	v_sub_f32_e32 v224, v224, v114
	v_sub_f32_e32 v225, v225, v114
	v_sub_f32_e32 v226, v226, v114
	v_sub_f32_e32 v227, v227, v114
	v_sub_f32_e32 v228, v228, v114
	v_sub_f32_e32 v229, v229, v114
	v_exp_f32_e32 v222, v222
	v_exp_f32_e32 v223, v223
	v_exp_f32_e32 v224, v224
	v_exp_f32_e32 v225, v225
	v_exp_f32_e32 v226, v226
	v_exp_f32_e32 v227, v227
	v_exp_f32_e32 v228, v228
	v_exp_f32_e32 v229, v229
	v_cvt_pk_bf16_f32 v118, v222, v223
	v_cvt_pk_bf16_f32 v119, v224, v225
	v_cvt_pk_bf16_f32 v120, v226, v227
	v_cvt_pk_bf16_f32 v121, v228, v229
	v_add_f32_e32 v116, v116, v222
	v_add_f32_e32 v117, v117, v223
	v_add_f32_e32 v116, v116, v224
	v_add_f32_e32 v117, v117, v225
	v_add_f32_e32 v116, v116, v226
	v_add_f32_e32 v117, v117, v227
	v_add_f32_e32 v116, v116, v228
	v_add_f32_e32 v117, v117, v229
	v_mfma_f32_32x32x16_bf16 v[18:33], v[182:185], v[118:121], v[18:33]
	v_mfma_f32_32x32x16_bf16 v[2:17], v[186:189], v[118:121], v[2:17]
	v_sub_f32_e32 v230, v230, v114
	v_sub_f32_e32 v231, v231, v114
	v_sub_f32_e32 v232, v232, v114
	v_sub_f32_e32 v233, v233, v114
	v_sub_f32_e32 v234, v234, v114
	v_sub_f32_e32 v235, v235, v114
	v_sub_f32_e32 v236, v236, v114
	v_sub_f32_e32 v237, v237, v114
	v_exp_f32_e32 v230, v230
	v_exp_f32_e32 v231, v231
	v_exp_f32_e32 v232, v232
	v_exp_f32_e32 v233, v233
	v_exp_f32_e32 v234, v234
	v_exp_f32_e32 v235, v235
	v_exp_f32_e32 v236, v236
	v_exp_f32_e32 v237, v237
	v_cvt_pk_bf16_f32 v118, v230, v231
	v_cvt_pk_bf16_f32 v119, v232, v233
	v_cvt_pk_bf16_f32 v120, v234, v235
	v_cvt_pk_bf16_f32 v121, v236, v237
	v_add_f32_e32 v116, v116, v230
	v_add_f32_e32 v117, v117, v231
	v_add_f32_e32 v116, v116, v232
	v_add_f32_e32 v117, v117, v233
	v_add_f32_e32 v116, v116, v234
	v_add_f32_e32 v117, v117, v235
	v_add_f32_e32 v116, v116, v236
	v_add_f32_e32 v117, v117, v237
	v_mfma_f32_32x32x16_bf16 v[18:33], v[190:193], v[118:121], v[18:33]
	v_mfma_f32_32x32x16_bf16 v[2:17], v[194:197], v[118:121], v[2:17]
	v_add_f32_e32 v116, v116, v117
	v_add_f32_e32 v109, v109, v116
